# grid-barrier poll loops: s_sleep removed (tighter release detection), on top of P0 absmax round pipelining
# speedup vs baseline: 1.0049x; 1.0026x over previous
; __device__ __forceinline__ unsigned xb_ld(unsigned* p)              { return __hip_atomic_load(p, __ATOMIC_RELAXED, __HIP_MEMORY_SCOPE_AGENT); }
; __device__ __forceinline__ void xcd_barrier_complete(unsigned* bar, unsigned x, unsigned& nloc, unsigned& nx) {
;     ...
;     for (;;) {
;         sum = 0u; cnt = 0u; mine = 0u;
; #pragma unroll
;         for (unsigned j = 0; j < 16; ++j) { const unsigned c = xb_ld(&bar[XB_XCNT(j)]); sum += c; cnt += (c > 0u) ? 1u : 0u; mine = (j == x) ? c : mine; }
;         if (sum == G) break;
;         __builtin_amdgcn_s_sleep(1);
;         if ((++sp & 255u) == 0u) { if (xb_ld(&bar[XB_TMO])) break; if (sp > XB_SPIN_CAP) { atomicAdd(&bar[XB_TMO], 1u); break; } }
;     }
.LBB0_350:
	v_readlane_b32 s2, v254, 11
	v_readlane_b32 s3, v254, 12
	s_mov_b64 s[14:15], -1
	s_nop 3
	global_load_dword v1, v17, s[2:3] sc1
	v_readlane_b32 s2, v254, 13
	v_readlane_b32 s3, v254, 14
	s_nop 4
	global_load_dword v2, v17, s[2:3] sc1
	v_readlane_b32 s2, v254, 15
	v_readlane_b32 s3, v254, 16
	s_nop 1
	s_nop 2
	global_load_dword v3, v17, s[2:3] sc1
	v_readlane_b32 s2, v254, 17
	v_readlane_b32 s3, v254, 18
	s_nop 1
	s_nop 2
	global_load_dword v4, v17, s[2:3] sc1
	v_readlane_b32 s2, v254, 19
	v_readlane_b32 s3, v254, 20
	s_nop 1
	s_nop 2
	global_load_dword v5, v17, s[2:3] sc1
	v_readlane_b32 s2, v254, 21
	v_readlane_b32 s3, v254, 22
	s_nop 1
	s_nop 2
	global_load_dword v6, v17, s[2:3] sc1
	v_readlane_b32 s2, v254, 23
	v_readlane_b32 s3, v254, 24
	s_nop 1
	s_nop 2
	global_load_dword v7, v17, s[2:3] sc1
	v_readlane_b32 s2, v254, 25
	v_readlane_b32 s3, v254, 26
	s_nop 1
	s_nop 2
	global_load_dword v8, v17, s[2:3] sc1
	v_readlane_b32 s2, v254, 27
	v_readlane_b32 s3, v254, 28
	s_nop 1
	s_nop 2
	global_load_dword v9, v17, s[2:3] sc1
	v_readlane_b32 s2, v254, 29
	v_readlane_b32 s3, v254, 30
	s_nop 1
	s_nop 2
	global_load_dword v10, v17, s[2:3] sc1
	v_readlane_b32 s2, v254, 31
	v_readlane_b32 s3, v254, 32
	s_nop 1
	s_nop 2
	global_load_dword v11, v17, s[2:3] sc1
	v_readlane_b32 s2, v254, 33
	v_readlane_b32 s3, v254, 34
	s_nop 1
	s_nop 2
	global_load_dword v12, v17, s[2:3] sc1
	v_readlane_b32 s2, v254, 35
	v_readlane_b32 s3, v254, 36
	s_nop 1
	s_nop 2
	global_load_dword v13, v17, s[2:3] sc1
	v_readlane_b32 s2, v254, 37
	v_readlane_b32 s3, v254, 38
	s_nop 1
	s_nop 2
	global_load_dword v14, v17, s[2:3] sc1
	v_readlane_b32 s2, v254, 39
	v_readlane_b32 s3, v254, 40
	s_nop 1
	s_nop 2
	global_load_dword v15, v17, s[2:3] sc1
	v_readlane_b32 s2, v254, 41
	v_readlane_b32 s3, v254, 42
	s_nop 1
	s_nop 2
	global_load_dword v16, v17, s[2:3] sc1
	s_mov_b64 s[2:3], -1
	s_nop 1
	s_waitcnt vmcnt(0)
	v_add_u32_e32 v18, v2, v1
	v_add_u32_e32 v18, v18, v3
	v_add_u32_e32 v18, v18, v4
	v_add_u32_e32 v18, v18, v5
	v_add_u32_e32 v18, v18, v6
	v_add_u32_e32 v18, v18, v7
	v_add_u32_e32 v18, v18, v8
	v_add_u32_e32 v18, v18, v9
	v_add_u32_e32 v18, v18, v10
	v_add_u32_e32 v18, v18, v11
	v_add_u32_e32 v18, v18, v12
	v_add_u32_e32 v18, v18, v13
	v_add_u32_e32 v18, v18, v14
	v_add_u32_e32 v18, v18, v15
	v_add_u32_e32 v18, v18, v16
	v_cmp_eq_u32_e32 vcc, s4, v18
	s_cbranch_vccnz .LBB0_349
	s_and_b32 s2, s5, 0xff
	s_cmp_eq_u32 s2, 0
	s_mov_b64 s[2:3], -1
	s_mov_b64 s[18:19], -1
	s_cbranch_scc1 .LBB0_354
	s_and_b64 vcc, exec, s[18:19]
	s_cbranch_vccz .LBB0_349

; __device__ __forceinline__ unsigned xb_ld(unsigned* p)              { return __hip_atomic_load(p, __ATOMIC_RELAXED, __HIP_MEMORY_SCOPE_AGENT); }
; __device__ __forceinline__ unsigned xb_add(unsigned* p, unsigned v) { return __hip_atomic_fetch_add(p, v, __ATOMIC_RELAXED, __HIP_MEMORY_SCOPE_AGENT); }
; #define XB_SPIN(cond, bar) do { unsigned _sp = 0; while (cond) { __builtin_amdgcn_s_sleep(1); \
;     if ((++_sp & 255u) == 0u) { if (xb_ld(&(bar)[XB_TMO])) break; if (_sp > XB_SPIN_CAP) { atomicAdd(&(bar)[XB_TMO], 1u); break; } } } } while (0)
; __device__ __forceinline__ void xcd_barrier(const XcdBarrier& b) {
;     ...
;             else XB_SPIN(xb_ld(&bar[XB_TOPGEN]) == tg, bar);
;             __builtin_amdgcn_fence(__ATOMIC_ACQUIRE, "agent");
;             xb_add(&bar[XB_XGEN(b.x)], 1u);
;             asm volatile("s_waitcnt vmcnt(0)" ::: "memory");
;         } else {
;             XB_SPIN(xb_ld(&bar[XB_XGEN(b.x)]) == gen, bar);
.LBB0_368:
	s_and_b32 s5, s4, 0xff
	s_mov_b64 s[22:23], -1
	s_cmp_lg_u32 s5, 0
	s_mov_b64 s[26:27], -1
	s_cbranch_scc0 .LBB0_371
	s_and_b64 vcc, exec, s[26:27]
	s_cbranch_vccz .LBB0_367

; __device__ __forceinline__ unsigned xb_ld(unsigned* p)              { return __hip_atomic_load(p, __ATOMIC_RELAXED, __HIP_MEMORY_SCOPE_AGENT); }
; __device__ __forceinline__ unsigned xb_add(unsigned* p, unsigned v) { return __hip_atomic_fetch_add(p, v, __ATOMIC_RELAXED, __HIP_MEMORY_SCOPE_AGENT); }
; #define XB_SPIN(cond, bar) do { unsigned _sp = 0; while (cond) { __builtin_amdgcn_s_sleep(1); \
;     if ((++_sp & 255u) == 0u) { if (xb_ld(&(bar)[XB_TMO])) break; if (_sp > XB_SPIN_CAP) { atomicAdd(&(bar)[XB_TMO], 1u); break; } } } } while (0)
; __device__ __forceinline__ void xcd_barrier(const XcdBarrier& b) {
;     ...
;             else XB_SPIN(xb_ld(&bar[XB_TOPGEN]) == tg, bar);
;             __builtin_amdgcn_fence(__ATOMIC_ACQUIRE, "agent");
;             xb_add(&bar[XB_XGEN(b.x)], 1u);
;             asm volatile("s_waitcnt vmcnt(0)" ::: "memory");
;         } else {
;             XB_SPIN(xb_ld(&bar[XB_XGEN(b.x)]) == gen, bar);
.LBB0_385:
	s_and_b32 s5, s4, 0xff
	s_cmp_lg_u32 s5, 0
	s_mov_b64 s[24:25], -1
	s_cbranch_scc0 .LBB0_388
	s_mov_b64 s[26:27], -1
	s_and_b64 vcc, exec, s[24:25]
	s_cbranch_vccz .LBB0_384

; __device__ __forceinline__ unsigned xb_ld(unsigned* p)              { return __hip_atomic_load(p, __ATOMIC_RELAXED, __HIP_MEMORY_SCOPE_AGENT); }
; __device__ __forceinline__ void xcd_barrier_complete(unsigned* bar, unsigned x, unsigned& nloc, unsigned& nx) {
;     ...
;     for (;;) {
;         sum = 0u; cnt = 0u; mine = 0u;
; #pragma unroll
;         for (unsigned j = 0; j < 16; ++j) { const unsigned c = xb_ld(&bar[XB_XCNT(j)]); sum += c; cnt += (c > 0u) ? 1u : 0u; mine = (j == x) ? c : mine; }
;         if (sum == G) break;
;         __builtin_amdgcn_s_sleep(1);
;         if ((++sp & 255u) == 0u) { if (xb_ld(&bar[XB_TMO])) break; if (sp > XB_SPIN_CAP) { atomicAdd(&bar[XB_TMO], 1u); break; } }
;     }
.LBB0_620:
	v_readlane_b32 s10, v254, 11
	v_readlane_b32 s11, v254, 12
	s_mov_b64 s[26:27], -1
	s_mov_b64 s[28:29], -1
	s_nop 2
	global_load_dword v2, v35, s[10:11] sc1
	v_readlane_b32 s10, v254, 13
	v_readlane_b32 s11, v254, 14
	s_nop 4
	global_load_dword v3, v35, s[10:11] sc1
	v_readlane_b32 s10, v254, 15
	v_readlane_b32 s11, v254, 16
	s_waitcnt vmcnt(0)
	v_add_u32_e32 v18, v3, v2
	s_nop 2
	global_load_dword v4, v35, s[10:11] sc1
	v_readlane_b32 s10, v254, 17
	v_readlane_b32 s11, v254, 18
	s_waitcnt vmcnt(0)
	v_add_u32_e32 v18, v18, v4
	s_nop 2
	global_load_dword v5, v35, s[10:11] sc1
	v_readlane_b32 s10, v254, 19
	v_readlane_b32 s11, v254, 20
	s_waitcnt vmcnt(0)
	v_add_u32_e32 v18, v18, v5
	s_nop 2
	global_load_dword v6, v35, s[10:11] sc1
	v_readlane_b32 s10, v254, 21
	v_readlane_b32 s11, v254, 22
	s_waitcnt vmcnt(0)
	v_add_u32_e32 v18, v18, v6
	s_nop 2
	global_load_dword v7, v35, s[10:11] sc1
	v_readlane_b32 s10, v254, 23
	v_readlane_b32 s11, v254, 24
	s_waitcnt vmcnt(0)
	v_add_u32_e32 v18, v18, v7
	s_nop 2
	global_load_dword v8, v35, s[10:11] sc1
	v_readlane_b32 s10, v254, 25
	v_readlane_b32 s11, v254, 26
	s_waitcnt vmcnt(0)
	v_add_u32_e32 v18, v18, v8
	s_nop 2
	global_load_dword v9, v35, s[10:11] sc1
	v_readlane_b32 s10, v254, 27
	v_readlane_b32 s11, v254, 28
	s_waitcnt vmcnt(0)
	v_add_u32_e32 v18, v18, v9
	s_nop 2
	global_load_dword v10, v35, s[10:11] sc1
	v_readlane_b32 s10, v254, 29
	v_readlane_b32 s11, v254, 30
	s_waitcnt vmcnt(0)
	v_add_u32_e32 v18, v18, v10
	s_nop 2
	global_load_dword v11, v35, s[10:11] sc1
	v_readlane_b32 s10, v254, 31
	v_readlane_b32 s11, v254, 32
	s_waitcnt vmcnt(0)
	v_add_u32_e32 v18, v18, v11
	s_nop 2
	global_load_dword v12, v35, s[10:11] sc1
	v_readlane_b32 s10, v254, 33
	v_readlane_b32 s11, v254, 34
	s_waitcnt vmcnt(0)
	v_add_u32_e32 v18, v18, v12
	s_nop 2
	global_load_dword v13, v35, s[10:11] sc1
	v_readlane_b32 s10, v254, 35
	v_readlane_b32 s11, v254, 36
	s_waitcnt vmcnt(0)
	v_add_u32_e32 v18, v18, v13
	s_nop 2
	global_load_dword v14, v35, s[10:11] sc1
	v_readlane_b32 s10, v254, 37
	v_readlane_b32 s11, v254, 38
	s_waitcnt vmcnt(0)
	v_add_u32_e32 v18, v18, v14
	s_nop 2
	global_load_dword v15, v35, s[10:11] sc1
	v_readlane_b32 s10, v254, 39
	v_readlane_b32 s11, v254, 40
	s_waitcnt vmcnt(0)
	v_add_u32_e32 v18, v18, v15
	s_nop 2
	global_load_dword v16, v35, s[10:11] sc1
	v_readlane_b32 s10, v254, 41
	v_readlane_b32 s11, v254, 42
	s_waitcnt vmcnt(0)
	v_add_u32_e32 v18, v18, v16
	s_nop 2
	global_load_dword v17, v35, s[10:11] sc1
	s_waitcnt vmcnt(0)
	v_add_u32_e32 v18, v18, v17
	v_cmp_eq_u32_e32 vcc, s8, v18
	s_cbranch_vccnz .LBB0_619
	s_and_b32 s10, s9, 0xff
	s_cmp_eq_u32 s10, 0
	s_mov_b64 s[30:31], -1
	s_cbranch_scc1 .LBB0_624
	s_and_b64 vcc, exec, s[30:31]
	s_cbranch_vccz .LBB0_619

; __device__ __forceinline__ unsigned xb_ld(unsigned* p)              { return __hip_atomic_load(p, __ATOMIC_RELAXED, __HIP_MEMORY_SCOPE_AGENT); }
; __device__ __forceinline__ unsigned xb_add(unsigned* p, unsigned v) { return __hip_atomic_fetch_add(p, v, __ATOMIC_RELAXED, __HIP_MEMORY_SCOPE_AGENT); }
; #define XB_SPIN(cond, bar) do { unsigned _sp = 0; while (cond) { __builtin_amdgcn_s_sleep(1); \
;     if ((++_sp & 255u) == 0u) { if (xb_ld(&(bar)[XB_TMO])) break; if (_sp > XB_SPIN_CAP) { atomicAdd(&(bar)[XB_TMO], 1u); break; } } } } while (0)
; __device__ __forceinline__ void xcd_barrier(const XcdBarrier& b) {
;     ...
;             else XB_SPIN(xb_ld(&bar[XB_TOPGEN]) == tg, bar);
;             __builtin_amdgcn_fence(__ATOMIC_ACQUIRE, "agent");
;             xb_add(&bar[XB_XGEN(b.x)], 1u);
;             asm volatile("s_waitcnt vmcnt(0)" ::: "memory");
;         } else {
;             XB_SPIN(xb_ld(&bar[XB_XGEN(b.x)]) == gen, bar);
.LBB0_638:
	s_and_b32 s9, s8, 0xff
	s_mov_b64 s[38:39], -1
	s_cmp_lg_u32 s9, 0
	s_mov_b64 s[42:43], -1
	s_cbranch_scc0 .LBB0_641
	s_and_b64 vcc, exec, s[42:43]
	s_cbranch_vccz .LBB0_637

; __device__ __forceinline__ unsigned xb_ld(unsigned* p)              { return __hip_atomic_load(p, __ATOMIC_RELAXED, __HIP_MEMORY_SCOPE_AGENT); }
; __device__ __forceinline__ void xcd_barrier_complete(unsigned* bar, unsigned x, unsigned& nloc, unsigned& nx) {
;     ...
;     for (;;) {
;         sum = 0u; cnt = 0u; mine = 0u;
; #pragma unroll
;         for (unsigned j = 0; j < 16; ++j) { const unsigned c = xb_ld(&bar[XB_XCNT(j)]); sum += c; cnt += (c > 0u) ? 1u : 0u; mine = (j == x) ? c : mine; }
;         if (sum == G) break;
;         __builtin_amdgcn_s_sleep(1);
;         if ((++sp & 255u) == 0u) { if (xb_ld(&bar[XB_TMO])) break; if (sp > XB_SPIN_CAP) { atomicAdd(&bar[XB_TMO], 1u); break; } }
;     }
.LBB0_858:
	v_readlane_b32 s10, v254, 11
	v_readlane_b32 s11, v254, 12
	s_mov_b64 s[26:27], -1
	s_mov_b64 s[28:29], -1
	s_nop 2
	global_load_dword v2, v35, s[10:11] sc1
	v_readlane_b32 s10, v254, 13
	v_readlane_b32 s11, v254, 14
	s_nop 4
	global_load_dword v3, v35, s[10:11] sc1
	v_readlane_b32 s10, v254, 15
	v_readlane_b32 s11, v254, 16
	s_waitcnt vmcnt(0)
	v_add_u32_e32 v18, v3, v2
	s_nop 2
	global_load_dword v4, v35, s[10:11] sc1
	v_readlane_b32 s10, v254, 17
	v_readlane_b32 s11, v254, 18
	s_waitcnt vmcnt(0)
	v_add_u32_e32 v18, v18, v4
	s_nop 2
	global_load_dword v5, v35, s[10:11] sc1
	v_readlane_b32 s10, v254, 19
	v_readlane_b32 s11, v254, 20
	s_waitcnt vmcnt(0)
	v_add_u32_e32 v18, v18, v5
	s_nop 2
	global_load_dword v6, v35, s[10:11] sc1
	v_readlane_b32 s10, v254, 21
	v_readlane_b32 s11, v254, 22
	s_waitcnt vmcnt(0)
	v_add_u32_e32 v18, v18, v6
	s_nop 2
	global_load_dword v7, v35, s[10:11] sc1
	v_readlane_b32 s10, v254, 23
	v_readlane_b32 s11, v254, 24
	s_waitcnt vmcnt(0)
	v_add_u32_e32 v18, v18, v7
	s_nop 2
	global_load_dword v8, v35, s[10:11] sc1
	v_readlane_b32 s10, v254, 25
	v_readlane_b32 s11, v254, 26
	s_waitcnt vmcnt(0)
	v_add_u32_e32 v18, v18, v8
	s_nop 2
	global_load_dword v9, v35, s[10:11] sc1
	v_readlane_b32 s10, v254, 27
	v_readlane_b32 s11, v254, 28
	s_waitcnt vmcnt(0)
	v_add_u32_e32 v18, v18, v9
	s_nop 2
	global_load_dword v10, v35, s[10:11] sc1
	v_readlane_b32 s10, v254, 29
	v_readlane_b32 s11, v254, 30
	s_waitcnt vmcnt(0)
	v_add_u32_e32 v18, v18, v10
	s_nop 2
	global_load_dword v11, v35, s[10:11] sc1
	v_readlane_b32 s10, v254, 31
	v_readlane_b32 s11, v254, 32
	s_waitcnt vmcnt(0)
	v_add_u32_e32 v18, v18, v11
	s_nop 2
	global_load_dword v12, v35, s[10:11] sc1
	v_readlane_b32 s10, v254, 33
	v_readlane_b32 s11, v254, 34
	s_waitcnt vmcnt(0)
	v_add_u32_e32 v18, v18, v12
	s_nop 2
	global_load_dword v13, v35, s[10:11] sc1
	v_readlane_b32 s10, v254, 35
	v_readlane_b32 s11, v254, 36
	s_waitcnt vmcnt(0)
	v_add_u32_e32 v18, v18, v13
	s_nop 2
	global_load_dword v14, v35, s[10:11] sc1
	v_readlane_b32 s10, v254, 37
	v_readlane_b32 s11, v254, 38
	s_waitcnt vmcnt(0)
	v_add_u32_e32 v18, v18, v14
	s_nop 2
	global_load_dword v15, v35, s[10:11] sc1
	v_readlane_b32 s10, v254, 39
	v_readlane_b32 s11, v254, 40
	s_waitcnt vmcnt(0)
	v_add_u32_e32 v18, v18, v15
	s_nop 2
	global_load_dword v16, v35, s[10:11] sc1
	v_readlane_b32 s10, v254, 41
	v_readlane_b32 s11, v254, 42
	s_waitcnt vmcnt(0)
	v_add_u32_e32 v18, v18, v16
	s_nop 2
	global_load_dword v17, v35, s[10:11] sc1
	s_waitcnt vmcnt(0)
	v_add_u32_e32 v18, v18, v17
	v_cmp_eq_u32_e32 vcc, s7, v18
	s_cbranch_vccnz .LBB0_857
	s_and_b32 s9, s8, 0xff
	s_cmp_eq_u32 s9, 0
	s_mov_b64 s[30:31], -1
	s_cbranch_scc1 .LBB0_862
	s_and_b64 vcc, exec, s[30:31]
	s_cbranch_vccz .LBB0_857

; __device__ __forceinline__ unsigned xb_ld(unsigned* p)              { return __hip_atomic_load(p, __ATOMIC_RELAXED, __HIP_MEMORY_SCOPE_AGENT); }
; __device__ __forceinline__ unsigned xb_add(unsigned* p, unsigned v) { return __hip_atomic_fetch_add(p, v, __ATOMIC_RELAXED, __HIP_MEMORY_SCOPE_AGENT); }
; #define XB_SPIN(cond, bar) do { unsigned _sp = 0; while (cond) { __builtin_amdgcn_s_sleep(1); \
;     if ((++_sp & 255u) == 0u) { if (xb_ld(&(bar)[XB_TMO])) break; if (_sp > XB_SPIN_CAP) { atomicAdd(&(bar)[XB_TMO], 1u); break; } } } } while (0)
; __device__ __forceinline__ void xcd_barrier(const XcdBarrier& b) {
;     ...
;             else XB_SPIN(xb_ld(&bar[XB_TOPGEN]) == tg, bar);
;             __builtin_amdgcn_fence(__ATOMIC_ACQUIRE, "agent");
;             xb_add(&bar[XB_XGEN(b.x)], 1u);
;             asm volatile("s_waitcnt vmcnt(0)" ::: "memory");
;         } else {
;             XB_SPIN(xb_ld(&bar[XB_XGEN(b.x)]) == gen, bar);
.LBB0_876:
	s_and_b32 s8, s7, 0xff
	s_mov_b64 s[38:39], -1
	s_cmp_lg_u32 s8, 0
	s_mov_b64 s[42:43], -1
	s_cbranch_scc0 .LBB0_879
	s_and_b64 vcc, exec, s[42:43]
	s_cbranch_vccz .LBB0_875

; __device__ __forceinline__ unsigned xb_ld(unsigned* p)              { return __hip_atomic_load(p, __ATOMIC_RELAXED, __HIP_MEMORY_SCOPE_AGENT); }
; __device__ __forceinline__ void xcd_barrier_complete(unsigned* bar, unsigned x, unsigned& nloc, unsigned& nx) {
;     ...
;     for (;;) {
;         sum = 0u; cnt = 0u; mine = 0u;
; #pragma unroll
;         for (unsigned j = 0; j < 16; ++j) { const unsigned c = xb_ld(&bar[XB_XCNT(j)]); sum += c; cnt += (c > 0u) ? 1u : 0u; mine = (j == x) ? c : mine; }
;         if (sum == G) break;
;         __builtin_amdgcn_s_sleep(1);
;         if ((++sp & 255u) == 0u) { if (xb_ld(&bar[XB_TMO])) break; if (sp > XB_SPIN_CAP) { atomicAdd(&bar[XB_TMO], 1u); break; } }
;     }
.LBB0_1679:
	v_readlane_b32 s10, v254, 11
	v_readlane_b32 s11, v254, 12
	s_mov_b64 s[26:27], -1
	s_mov_b64 s[28:29], -1
	s_nop 2
	global_load_dword v2, v35, s[10:11] sc1
	v_readlane_b32 s10, v254, 13
	v_readlane_b32 s11, v254, 14
	s_nop 4
	global_load_dword v3, v35, s[10:11] sc1
	v_readlane_b32 s10, v254, 15
	v_readlane_b32 s11, v254, 16
	s_waitcnt vmcnt(0)
	v_add_u32_e32 v18, v3, v2
	s_nop 2
	global_load_dword v4, v35, s[10:11] sc1
	v_readlane_b32 s10, v254, 17
	v_readlane_b32 s11, v254, 18
	s_waitcnt vmcnt(0)
	v_add_u32_e32 v18, v18, v4
	s_nop 2
	global_load_dword v5, v35, s[10:11] sc1
	v_readlane_b32 s10, v254, 19
	v_readlane_b32 s11, v254, 20
	s_waitcnt vmcnt(0)
	v_add_u32_e32 v18, v18, v5
	s_nop 2
	global_load_dword v6, v35, s[10:11] sc1
	v_readlane_b32 s10, v254, 21
	v_readlane_b32 s11, v254, 22
	s_waitcnt vmcnt(0)
	v_add_u32_e32 v18, v18, v6
	s_nop 2
	global_load_dword v7, v35, s[10:11] sc1
	v_readlane_b32 s10, v254, 23
	v_readlane_b32 s11, v254, 24
	s_waitcnt vmcnt(0)
	v_add_u32_e32 v18, v18, v7
	s_nop 2
	global_load_dword v8, v35, s[10:11] sc1
	v_readlane_b32 s10, v254, 25
	v_readlane_b32 s11, v254, 26
	s_waitcnt vmcnt(0)
	v_add_u32_e32 v18, v18, v8
	s_nop 2
	global_load_dword v9, v35, s[10:11] sc1
	v_readlane_b32 s10, v254, 27
	v_readlane_b32 s11, v254, 28
	s_waitcnt vmcnt(0)
	v_add_u32_e32 v18, v18, v9
	s_nop 2
	global_load_dword v10, v35, s[10:11] sc1
	v_readlane_b32 s10, v254, 29
	v_readlane_b32 s11, v254, 30
	s_waitcnt vmcnt(0)
	v_add_u32_e32 v18, v18, v10
	s_nop 2
	global_load_dword v11, v35, s[10:11] sc1
	v_readlane_b32 s10, v254, 31
	v_readlane_b32 s11, v254, 32
	s_waitcnt vmcnt(0)
	v_add_u32_e32 v18, v18, v11
	s_nop 2
	global_load_dword v12, v35, s[10:11] sc1
	v_readlane_b32 s10, v254, 33
	v_readlane_b32 s11, v254, 34
	s_waitcnt vmcnt(0)
	v_add_u32_e32 v18, v18, v12
	s_nop 2
	global_load_dword v13, v35, s[10:11] sc1
	v_readlane_b32 s10, v254, 35
	v_readlane_b32 s11, v254, 36
	s_waitcnt vmcnt(0)
	v_add_u32_e32 v18, v18, v13
	s_nop 2
	global_load_dword v14, v35, s[10:11] sc1
	v_readlane_b32 s10, v254, 37
	v_readlane_b32 s11, v254, 38
	s_waitcnt vmcnt(0)
	v_add_u32_e32 v18, v18, v14
	s_nop 2
	global_load_dword v15, v35, s[10:11] sc1
	v_readlane_b32 s10, v254, 39
	v_readlane_b32 s11, v254, 40
	s_waitcnt vmcnt(0)
	v_add_u32_e32 v18, v18, v15
	s_nop 2
	global_load_dword v16, v35, s[10:11] sc1
	v_readlane_b32 s10, v254, 41
	v_readlane_b32 s11, v254, 42
	s_waitcnt vmcnt(0)
	v_add_u32_e32 v18, v18, v16
	s_nop 2
	global_load_dword v17, v35, s[10:11] sc1
	s_waitcnt vmcnt(0)
	v_add_u32_e32 v18, v18, v17
	v_cmp_eq_u32_e32 vcc, s6, v18
	s_cbranch_vccnz .LBB0_1678
	s_and_b32 s9, s8, 0xff
	s_cmp_eq_u32 s9, 0
	s_mov_b64 s[30:31], -1
	s_cbranch_scc1 .LBB0_1683
	s_and_b64 vcc, exec, s[30:31]
	s_cbranch_vccz .LBB0_1678

; __device__ __forceinline__ unsigned xb_ld(unsigned* p)              { return __hip_atomic_load(p, __ATOMIC_RELAXED, __HIP_MEMORY_SCOPE_AGENT); }
; __device__ __forceinline__ unsigned xb_add(unsigned* p, unsigned v) { return __hip_atomic_fetch_add(p, v, __ATOMIC_RELAXED, __HIP_MEMORY_SCOPE_AGENT); }
; #define XB_SPIN(cond, bar) do { unsigned _sp = 0; while (cond) { __builtin_amdgcn_s_sleep(1); \
;     if ((++_sp & 255u) == 0u) { if (xb_ld(&(bar)[XB_TMO])) break; if (_sp > XB_SPIN_CAP) { atomicAdd(&(bar)[XB_TMO], 1u); break; } } } } while (0)
; __device__ __forceinline__ void xcd_barrier(const XcdBarrier& b) {
;     ...
;             else XB_SPIN(xb_ld(&bar[XB_TOPGEN]) == tg, bar);
;             __builtin_amdgcn_fence(__ATOMIC_ACQUIRE, "agent");
;             xb_add(&bar[XB_XGEN(b.x)], 1u);
;             asm volatile("s_waitcnt vmcnt(0)" ::: "memory");
;         } else {
;             XB_SPIN(xb_ld(&bar[XB_XGEN(b.x)]) == gen, bar);
.LBB0_1697:
	s_and_b32 s8, s6, 0xff
	s_mov_b64 s[38:39], -1
	s_cmp_lg_u32 s8, 0
	s_mov_b64 s[42:43], -1
	s_cbranch_scc0 .LBB0_1700
	s_and_b64 vcc, exec, s[42:43]
	s_cbranch_vccz .LBB0_1696
